# cache-policy A/B: sample-attention K/V cache-row loads with the default policy instead of nt (rows are shared by the 4 tokens of a batch/head)
# speedup vs baseline: 1.0042x; 1.0042x over previous
.LBB0_564:
	s_cmpk_lt_i32 s16, 0x200
	s_cselect_b64 s[18:19], -1, 0
	s_bfe_u32 s4, s16, 0x30006
	s_bfe_u32 s23, s16, 0x20004
	s_lshl_b32 s5, s4, 2
	s_or_b32 s12, s5, s23
	s_and_b32 s13, s16, 15
	s_bitset1_b32 s12, 13
	s_cmpk_gt_i32 s16, 0x1ff
	s_mul_i32 s22, s12, 0x1800
	s_cbranch_scc1 .LBB0_570
	s_lshl_b32 s5, s22, 1
	s_add_u32 s5, s28, s5
	s_addc_u32 s7, s29, 0
	s_lshl_b32 s6, s13, 7
	s_add_u32 s6, s5, s6
	s_addc_u32 s7, s7, 0
	v_lshlrev_b32_e32 v0, 1, v96
	v_and_b32_e32 v1, 64, v182
	global_load_dwordx2 v[152:153], v0, s[6:7]
	v_xor_b32_e32 v0, 1, v182
	v_add_u32_e32 v101, 64, v1
	v_cmp_lt_i32_e32 vcc, v0, v101
	s_bitset1_b32 s23, 11
	s_lshl_b32 s93, s4, 11
	v_cndmask_b32_e32 v0, v182, v0, vcc
	v_lshlrev_b32_e32 v187, 2, v0
	v_xor_b32_e32 v0, 2, v182
	v_cmp_lt_i32_e32 vcc, v0, v101
	s_add_i32 s92, s93, -4
	v_mov_b32_e32 v190, s25
	v_cndmask_b32_e32 v0, v182, v0, vcc
	v_lshlrev_b32_e32 v186, 2, v0
	v_xor_b32_e32 v0, 4, v182
	v_cmp_lt_i32_e32 vcc, v0, v101
	v_mov_b32_e32 v191, s49
	v_mov_b32_e32 v192, s26
	v_cndmask_b32_e32 v0, v182, v0, vcc
	v_lshlrev_b32_e32 v185, 2, v0
	v_xor_b32_e32 v0, 8, v182
	v_cmp_lt_i32_e32 vcc, v0, v101
	v_mov_b32_e32 v193, s48
	s_lshl_b32 s36, s13, 8
	v_cndmask_b32_e32 v0, v182, v0, vcc
	v_lshlrev_b32_e32 v184, 2, v0
	v_sub_u32_e32 v0, s23, v97
	v_add_u32_e32 v3, s93, v0
	v_add_u32_e32 v2, s92, v0
	v_ashrrev_i32_e32 v1, 31, v3
	v_cmp_gt_i32_e64 s[4:5], s14, v0
	v_lshlrev_b32_e32 v98, 2, v96
	s_mov_b32 s24, s27
	v_cndmask_b32_e64 v1, 0, v1, s[4:5]
	v_cndmask_b32_e64 v0, v2, v3, s[4:5]
	v_cndmask_b32_e64 v3, v190, v191, s[4:5]
	v_cndmask_b32_e64 v2, v192, v193, s[4:5]
	v_lshlrev_b64 v[102:103], 12, v[0:1]
	v_lshl_add_u64 v[0:1], v[2:3], 0, v[102:103]
	v_lshl_add_u64 v[0:1], v[0:1], 0, s[36:37]
	v_lshl_add_u64 v[0:1], v[0:1], 0, v[98:99]
	global_load_dwordx4 v[92:95], v[0:1], off
	v_sub_u32_e32 v0, s23, v154
	v_add_u32_e32 v2, s93, v0
	v_ashrrev_i32_e32 v1, 31, v2
	v_add_u32_e32 v3, s92, v0
	v_cmp_gt_i32_e64 s[54:55], s14, v0
	s_mov_b32 s27, s97
	s_mov_b64 s[20:21], s[98:99]
	v_cndmask_b32_e64 v1, 0, v1, s[54:55]
	v_cndmask_b32_e64 v0, v3, v2, s[54:55]
	v_cndmask_b32_e64 v3, v190, v191, s[54:55]
	v_cndmask_b32_e64 v2, v192, v193, s[54:55]
	v_lshlrev_b64 v[104:105], 12, v[0:1]
	v_lshl_add_u64 v[0:1], v[2:3], 0, v[104:105]
	v_lshl_add_u64 v[0:1], v[0:1], 0, s[36:37]
	v_lshl_add_u64 v[0:1], v[0:1], 0, v[98:99]
	global_load_dwordx4 v[28:31], v[0:1], off
	v_sub_u32_e32 v0, s23, v155
	v_add_u32_e32 v2, s93, v0
	v_ashrrev_i32_e32 v1, 31, v2
	v_add_u32_e32 v3, s92, v0
	v_cmp_gt_i32_e64 s[56:57], s14, v0
	s_mov_b64 s[34:35], s[78:79]
	v_sub_u32_e32 v194, s23, v178
	v_cndmask_b32_e64 v1, 0, v1, s[56:57]
	v_cndmask_b32_e64 v0, v3, v2, s[56:57]
	v_cndmask_b32_e64 v3, v190, v191, s[56:57]
	v_cndmask_b32_e64 v2, v192, v193, s[56:57]
	v_lshlrev_b64 v[106:107], 12, v[0:1]
	v_lshl_add_u64 v[0:1], v[2:3], 0, v[106:107]
	v_lshl_add_u64 v[0:1], v[0:1], 0, s[36:37]
	v_lshl_add_u64 v[0:1], v[0:1], 0, v[98:99]
	global_load_dwordx4 v[88:91], v[0:1], off
	v_sub_u32_e32 v0, s23, v156
	v_add_u32_e32 v2, s93, v0
	v_ashrrev_i32_e32 v1, 31, v2
	v_add_u32_e32 v3, s92, v0
	v_cmp_gt_i32_e64 s[96:97], s14, v0
	v_add_u32_e32 v195, s93, v194
	s_waitcnt vmcnt(3)
	v_and_b32_e32 v150, 0xffff0000, v152
	v_cndmask_b32_e64 v1, 0, v1, s[96:97]
	v_cndmask_b32_e64 v0, v3, v2, s[96:97]
	v_cndmask_b32_e64 v3, v190, v191, s[96:97]
	v_cndmask_b32_e64 v2, v192, v193, s[96:97]
	v_lshlrev_b64 v[110:111], 12, v[0:1]
	v_lshl_add_u64 v[0:1], v[2:3], 0, v[110:111]
	v_lshl_add_u64 v[0:1], v[0:1], 0, s[36:37]
	v_lshl_add_u64 v[0:1], v[0:1], 0, v[98:99]
	global_load_dwordx4 v[84:87], v[0:1], off
	v_sub_u32_e32 v0, s23, v157
	v_add_u32_e32 v2, s93, v0
	v_ashrrev_i32_e32 v1, 31, v2
	v_add_u32_e32 v3, s92, v0
	v_cmp_gt_i32_e64 s[8:9], s14, v0
	v_lshlrev_b32_e32 v151, 16, v153
	v_lshlrev_b32_e32 v152, 16, v152
	v_cndmask_b32_e64 v1, 0, v1, s[8:9]
	v_cndmask_b32_e64 v0, v3, v2, s[8:9]
	v_cndmask_b32_e64 v3, v190, v191, s[8:9]
	v_cndmask_b32_e64 v2, v192, v193, s[8:9]
	v_lshlrev_b64 v[114:115], 12, v[0:1]
	v_lshl_add_u64 v[0:1], v[2:3], 0, v[114:115]
	v_lshl_add_u64 v[0:1], v[0:1], 0, s[36:37]
	v_lshl_add_u64 v[0:1], v[0:1], 0, v[98:99]
	global_load_dwordx4 v[80:83], v[0:1], off
	v_sub_u32_e32 v0, s23, v158
	v_add_u32_e32 v2, s93, v0
	v_ashrrev_i32_e32 v1, 31, v2
	v_add_u32_e32 v3, s92, v0
	v_cmp_gt_i32_e64 s[58:59], s14, v0
	v_and_b32_e32 v153, 0xffff0000, v153
	v_add_u32_e32 v197, s92, v194
	v_cndmask_b32_e64 v1, 0, v1, s[58:59]
	v_cndmask_b32_e64 v0, v3, v2, s[58:59]
	v_cndmask_b32_e64 v3, v190, v191, s[58:59]
	v_cndmask_b32_e64 v2, v192, v193, s[58:59]
	v_lshlrev_b64 v[108:109], 12, v[0:1]
	v_lshl_add_u64 v[0:1], v[2:3], 0, v[108:109]
	v_lshl_add_u64 v[0:1], v[0:1], 0, s[36:37]
	v_lshl_add_u64 v[0:1], v[0:1], 0, v[98:99]
	global_load_dwordx4 v[76:79], v[0:1], off
	v_sub_u32_e32 v0, s23, v159
	v_add_u32_e32 v2, s93, v0
	v_ashrrev_i32_e32 v1, 31, v2
	v_add_u32_e32 v3, s92, v0
	v_cmp_gt_i32_e64 s[98:99], s14, v0
	s_waitcnt vmcnt(5)
	v_mov_b32_e32 v188, v93
	v_mov_b32_e32 v93, v95
	v_cndmask_b32_e64 v1, 0, v1, s[98:99]
	v_cndmask_b32_e64 v0, v3, v2, s[98:99]
	v_cndmask_b32_e64 v3, v190, v191, s[98:99]
	v_cndmask_b32_e64 v2, v192, v193, s[98:99]
	v_lshlrev_b64 v[112:113], 12, v[0:1]
	v_lshl_add_u64 v[0:1], v[2:3], 0, v[112:113]
	v_lshl_add_u64 v[0:1], v[0:1], 0, s[36:37]
	v_lshl_add_u64 v[0:1], v[0:1], 0, v[98:99]
	global_load_dwordx4 v[72:75], v[0:1], off
	v_sub_u32_e32 v0, s23, v160
	v_add_u32_e32 v2, s93, v0
	v_ashrrev_i32_e32 v1, 31, v2
	v_add_u32_e32 v3, s92, v0
	v_cmp_gt_i32_e64 s[6:7], s14, v0
	v_mov_b32_e32 v189, v94
	v_pk_mul_f32 v[92:93], v[92:93], v[152:153]
	v_cndmask_b32_e64 v1, 0, v1, s[6:7]
	v_cndmask_b32_e64 v0, v3, v2, s[6:7]
	v_cndmask_b32_e64 v3, v190, v191, s[6:7]
	v_cndmask_b32_e64 v2, v192, v193, s[6:7]
	v_lshlrev_b64 v[116:117], 12, v[0:1]
	v_lshl_add_u64 v[0:1], v[2:3], 0, v[116:117]
	v_lshl_add_u64 v[0:1], v[0:1], 0, s[36:37]
	v_lshl_add_u64 v[0:1], v[0:1], 0, v[98:99]
	global_load_dwordx4 v[68:71], v[0:1], off
	v_sub_u32_e32 v0, s23, v161
	v_add_u32_e32 v2, s93, v0
	v_ashrrev_i32_e32 v1, 31, v2
	v_add_u32_e32 v3, s92, v0
	v_cmp_gt_i32_e64 s[60:61], s14, v0
	v_pk_fma_f32 v[92:93], v[188:189], v[150:151], v[92:93]
	v_ashrrev_i32_e32 v196, 31, v195
	v_cndmask_b32_e64 v1, 0, v1, s[60:61]
	v_cndmask_b32_e64 v0, v3, v2, s[60:61]
	v_cndmask_b32_e64 v3, v190, v191, s[60:61]
	v_cndmask_b32_e64 v2, v192, v193, s[60:61]
	v_lshlrev_b64 v[118:119], 12, v[0:1]
	v_lshl_add_u64 v[0:1], v[2:3], 0, v[118:119]
	v_lshl_add_u64 v[0:1], v[0:1], 0, s[36:37]
	v_lshl_add_u64 v[0:1], v[0:1], 0, v[98:99]
	global_load_dwordx4 v[64:67], v[0:1], off
	v_sub_u32_e32 v0, s23, v162
	v_add_u32_e32 v2, s93, v0
	v_ashrrev_i32_e32 v1, 31, v2
	v_add_u32_e32 v3, s92, v0
	v_cmp_gt_i32_e64 s[62:63], s14, v0
	v_add_f32_e32 v94, v92, v93
	ds_bpermute_b32 v188, v187, v94
	v_cndmask_b32_e64 v1, 0, v1, s[62:63]
	v_cndmask_b32_e64 v0, v3, v2, s[62:63]
	v_cndmask_b32_e64 v3, v190, v191, s[62:63]
	v_cndmask_b32_e64 v2, v192, v193, s[62:63]
	v_lshlrev_b64 v[120:121], 12, v[0:1]
	v_lshl_add_u64 v[0:1], v[2:3], 0, v[120:121]
	v_lshl_add_u64 v[0:1], v[0:1], 0, s[36:37]
	v_lshl_add_u64 v[0:1], v[0:1], 0, v[98:99]
	global_load_dwordx4 v[60:63], v[0:1], off
	v_sub_u32_e32 v0, s23, v163
	v_add_u32_e32 v2, s93, v0
	v_ashrrev_i32_e32 v1, 31, v2
	v_add_u32_e32 v3, s92, v0
	v_cmp_gt_i32_e32 vcc, s14, v0
	s_waitcnt lgkmcnt(0)
	v_add_f32_e32 v188, v94, v188
	ds_bpermute_b32 v189, v186, v188
	v_cndmask_b32_e32 v1, 0, v1, vcc
	v_cndmask_b32_e32 v0, v3, v2, vcc
	v_cndmask_b32_e32 v3, v190, v191, vcc
	v_cndmask_b32_e32 v2, v192, v193, vcc
	v_lshlrev_b64 v[122:123], 12, v[0:1]
	v_lshl_add_u64 v[0:1], v[2:3], 0, v[122:123]
	v_lshl_add_u64 v[0:1], v[0:1], 0, s[36:37]
	v_lshl_add_u64 v[0:1], v[0:1], 0, v[98:99]
	global_load_dwordx4 v[56:59], v[0:1], off
	v_sub_u32_e32 v0, s23, v164
	v_add_u32_e32 v2, s93, v0
	v_ashrrev_i32_e32 v1, 31, v2
	v_add_u32_e32 v3, s92, v0
	v_cmp_gt_i32_e64 s[10:11], s14, v0
	s_nop 1
	v_cndmask_b32_e64 v1, 0, v1, s[10:11]
	v_cndmask_b32_e64 v0, v3, v2, s[10:11]
	v_cndmask_b32_e64 v3, v190, v191, s[10:11]
	v_cndmask_b32_e64 v2, v192, v193, s[10:11]
	v_lshlrev_b64 v[124:125], 12, v[0:1]
	v_lshl_add_u64 v[0:1], v[2:3], 0, v[124:125]
	v_lshl_add_u64 v[0:1], v[0:1], 0, s[36:37]
	v_lshl_add_u64 v[0:1], v[0:1], 0, v[98:99]
	global_load_dwordx4 v[52:55], v[0:1], off
	v_sub_u32_e32 v0, s23, v165
	v_add_u32_e32 v2, s93, v0
	v_ashrrev_i32_e32 v1, 31, v2
	v_add_u32_e32 v3, s92, v0
	v_cmp_gt_i32_e64 s[70:71], s14, v0
	s_nop 1
	v_cndmask_b32_e64 v1, 0, v1, s[70:71]
	v_cndmask_b32_e64 v0, v3, v2, s[70:71]
	v_cndmask_b32_e64 v3, v190, v191, s[70:71]
	v_cndmask_b32_e64 v2, v192, v193, s[70:71]
	v_lshlrev_b64 v[128:129], 12, v[0:1]
	v_lshl_add_u64 v[0:1], v[2:3], 0, v[128:129]
	v_lshl_add_u64 v[0:1], v[0:1], 0, s[36:37]
	v_lshl_add_u64 v[0:1], v[0:1], 0, v[98:99]
	global_load_dwordx4 v[48:51], v[0:1], off
	v_sub_u32_e32 v0, s23, v166
	v_add_u32_e32 v2, s93, v0
	v_ashrrev_i32_e32 v1, 31, v2
	v_add_u32_e32 v3, s92, v0
	v_cmp_gt_i32_e64 s[74:75], s14, v0
	s_nop 1
	v_cndmask_b32_e64 v1, 0, v1, s[74:75]
	v_cndmask_b32_e64 v0, v3, v2, s[74:75]
	v_cndmask_b32_e64 v3, v190, v191, s[74:75]
	v_cndmask_b32_e64 v2, v192, v193, s[74:75]
	v_lshlrev_b64 v[132:133], 12, v[0:1]
	v_lshl_add_u64 v[0:1], v[2:3], 0, v[132:133]
	v_lshl_add_u64 v[0:1], v[0:1], 0, s[36:37]
	v_lshl_add_u64 v[0:1], v[0:1], 0, v[98:99]
	global_load_dwordx4 v[44:47], v[0:1], off
	v_sub_u32_e32 v0, s23, v167
	v_add_u32_e32 v2, s93, v0
	v_ashrrev_i32_e32 v1, 31, v2
	v_add_u32_e32 v3, s92, v0
	v_cmp_gt_i32_e64 s[78:79], s14, v0
	s_nop 1
	v_cndmask_b32_e64 v1, 0, v1, s[78:79]
	v_cndmask_b32_e64 v0, v3, v2, s[78:79]
	v_cndmask_b32_e64 v3, v190, v191, s[78:79]
	v_cndmask_b32_e64 v2, v192, v193, s[78:79]
	v_lshlrev_b64 v[136:137], 12, v[0:1]
	v_lshl_add_u64 v[0:1], v[2:3], 0, v[136:137]
	v_lshl_add_u64 v[0:1], v[0:1], 0, s[36:37]
	v_lshl_add_u64 v[0:1], v[0:1], 0, v[98:99]
	global_load_dwordx4 v[40:43], v[0:1], off
	v_sub_u32_e32 v0, s23, v168
	v_add_u32_e32 v2, s93, v0
	v_ashrrev_i32_e32 v1, 31, v2
	v_add_u32_e32 v3, s92, v0
	v_cmp_gt_i32_e64 s[82:83], s14, v0
	s_nop 1
	v_cndmask_b32_e64 v1, 0, v1, s[82:83]
	v_cndmask_b32_e64 v0, v3, v2, s[82:83]
	v_cndmask_b32_e64 v3, v190, v191, s[82:83]
	v_cndmask_b32_e64 v2, v192, v193, s[82:83]
	v_lshlrev_b64 v[140:141], 12, v[0:1]
	v_lshl_add_u64 v[0:1], v[2:3], 0, v[140:141]
	v_lshl_add_u64 v[0:1], v[0:1], 0, s[36:37]
	v_lshl_add_u64 v[0:1], v[0:1], 0, v[98:99]
	global_load_dwordx4 v[36:39], v[0:1], off
	v_sub_u32_e32 v0, s23, v170
	v_add_u32_e32 v2, s93, v0
	v_ashrrev_i32_e32 v1, 31, v2
	v_add_u32_e32 v3, s92, v0
	v_cmp_gt_i32_e64 s[68:69], s14, v0
	s_nop 1
	v_cndmask_b32_e64 v1, 0, v1, s[68:69]
	v_cndmask_b32_e64 v0, v3, v2, s[68:69]
	v_cndmask_b32_e64 v3, v190, v191, s[68:69]
	v_cndmask_b32_e64 v2, v192, v193, s[68:69]
	v_lshlrev_b64 v[126:127], 12, v[0:1]
	v_lshl_add_u64 v[0:1], v[2:3], 0, v[126:127]
	v_lshl_add_u64 v[0:1], v[0:1], 0, s[36:37]
	v_lshl_add_u64 v[0:1], v[0:1], 0, v[98:99]
	global_load_dwordx4 v[32:35], v[0:1], off
	v_sub_u32_e32 v0, s23, v171
	v_add_u32_e32 v2, s93, v0
	v_ashrrev_i32_e32 v1, 31, v2
	v_add_u32_e32 v3, s92, v0
	v_cmp_gt_i32_e64 s[72:73], s14, v0
	s_nop 1
	v_cndmask_b32_e64 v1, 0, v1, s[72:73]
	v_cndmask_b32_e64 v0, v3, v2, s[72:73]
	v_cndmask_b32_e64 v3, v190, v191, s[72:73]
	v_cndmask_b32_e64 v2, v192, v193, s[72:73]
	v_lshlrev_b64 v[130:131], 12, v[0:1]
	v_lshl_add_u64 v[0:1], v[2:3], 0, v[130:131]
	v_lshl_add_u64 v[0:1], v[0:1], 0, s[36:37]
	v_lshl_add_u64 v[0:1], v[0:1], 0, v[98:99]
	global_load_dwordx4 v[20:23], v[0:1], off
	v_sub_u32_e32 v0, s23, v172
	v_add_u32_e32 v2, s93, v0
	v_ashrrev_i32_e32 v1, 31, v2
	v_add_u32_e32 v3, s92, v0
	v_cmp_gt_i32_e64 s[76:77], s14, v0
	s_nop 1
	v_cndmask_b32_e64 v1, 0, v1, s[76:77]
	v_cndmask_b32_e64 v0, v3, v2, s[76:77]
	v_cndmask_b32_e64 v3, v190, v191, s[76:77]
	v_cndmask_b32_e64 v2, v192, v193, s[76:77]
	v_lshlrev_b64 v[134:135], 12, v[0:1]
	v_lshl_add_u64 v[0:1], v[2:3], 0, v[134:135]
	v_lshl_add_u64 v[0:1], v[0:1], 0, s[36:37]
	v_lshl_add_u64 v[0:1], v[0:1], 0, v[98:99]
	global_load_dwordx4 v[24:27], v[0:1], off
	v_sub_u32_e32 v0, s23, v173
	v_add_u32_e32 v2, s93, v0
	v_ashrrev_i32_e32 v1, 31, v2
	v_add_u32_e32 v3, s92, v0
	v_cmp_gt_i32_e64 s[80:81], s14, v0
	s_nop 1
	v_cndmask_b32_e64 v1, 0, v1, s[80:81]
	v_cndmask_b32_e64 v0, v3, v2, s[80:81]
	v_cndmask_b32_e64 v3, v190, v191, s[80:81]
	v_cndmask_b32_e64 v2, v192, v193, s[80:81]
	v_lshlrev_b64 v[138:139], 12, v[0:1]
	v_lshl_add_u64 v[0:1], v[2:3], 0, v[138:139]
	v_lshl_add_u64 v[0:1], v[0:1], 0, s[36:37]
	v_lshl_add_u64 v[0:1], v[0:1], 0, v[98:99]
	global_load_dwordx4 v[16:19], v[0:1], off
	v_sub_u32_e32 v0, s23, v174
	v_add_u32_e32 v2, s93, v0
	v_ashrrev_i32_e32 v1, 31, v2
	v_add_u32_e32 v3, s92, v0
	v_cmp_gt_i32_e64 s[84:85], s14, v0
	s_nop 1
	v_cndmask_b32_e64 v1, 0, v1, s[84:85]
	v_cndmask_b32_e64 v0, v3, v2, s[84:85]
	v_cndmask_b32_e64 v3, v190, v191, s[84:85]
	v_cndmask_b32_e64 v2, v192, v193, s[84:85]
	v_lshlrev_b64 v[142:143], 12, v[0:1]
	v_lshl_add_u64 v[0:1], v[2:3], 0, v[142:143]
	v_lshl_add_u64 v[0:1], v[0:1], 0, s[36:37]
	v_lshl_add_u64 v[0:1], v[0:1], 0, v[98:99]
	global_load_dwordx4 v[12:15], v[0:1], off
	v_sub_u32_e32 v0, s23, v175
	v_add_u32_e32 v2, s93, v0
	v_ashrrev_i32_e32 v1, 31, v2
	v_add_u32_e32 v3, s92, v0
	v_cmp_gt_i32_e64 s[86:87], s14, v0
	s_nop 1
	v_cndmask_b32_e64 v1, 0, v1, s[86:87]
	v_cndmask_b32_e64 v0, v3, v2, s[86:87]
	v_cndmask_b32_e64 v3, v190, v191, s[86:87]
	v_cndmask_b32_e64 v2, v192, v193, s[86:87]
	v_lshlrev_b64 v[144:145], 12, v[0:1]
	v_lshl_add_u64 v[0:1], v[2:3], 0, v[144:145]
	v_lshl_add_u64 v[0:1], v[0:1], 0, s[36:37]
	v_lshl_add_u64 v[0:1], v[0:1], 0, v[98:99]
	global_load_dwordx4 v[8:11], v[0:1], off
	v_sub_u32_e32 v0, s23, v176
	v_add_u32_e32 v2, s93, v0
	v_ashrrev_i32_e32 v1, 31, v2
	v_add_u32_e32 v3, s92, v0
	v_cmp_gt_i32_e64 s[88:89], s14, v0
	s_nop 1
	v_cndmask_b32_e64 v1, 0, v1, s[88:89]
	v_cndmask_b32_e64 v0, v3, v2, s[88:89]
	v_cndmask_b32_e64 v3, v190, v191, s[88:89]
	v_cndmask_b32_e64 v2, v192, v193, s[88:89]
	v_lshlrev_b64 v[146:147], 12, v[0:1]
	v_lshl_add_u64 v[0:1], v[2:3], 0, v[146:147]
	v_lshl_add_u64 v[0:1], v[0:1], 0, s[36:37]
	v_lshl_add_u64 v[0:1], v[0:1], 0, v[98:99]
	global_load_dwordx4 v[4:7], v[0:1], off
	v_sub_u32_e32 v0, s23, v177
	v_add_u32_e32 v2, s93, v0
	v_add_u32_e32 v3, s92, v0
	v_cmp_gt_i32_e64 s[90:91], s14, v0
	v_cmp_gt_i32_e64 s[92:93], s14, v194
	v_ashrrev_i32_e32 v1, 31, v2
	v_cndmask_b32_e64 v0, v3, v2, s[90:91]
	v_cndmask_b32_e64 v3, v190, v191, s[90:91]
	v_cndmask_b32_e64 v95, v190, v191, s[92:93]
	s_waitcnt lgkmcnt(0)
	v_add_f32_e32 v190, v188, v189
	s_waitcnt vmcnt(21)
	v_mov_b32_e32 v188, v29
	v_mov_b32_e32 v29, v31
	v_cndmask_b32_e64 v93, 0, v196, s[92:93]
	v_cndmask_b32_e64 v92, v197, v195, s[92:93]
	v_mov_b32_e32 v189, v30
	v_pk_mul_f32 v[28:29], v[28:29], v[152:153]
	v_cndmask_b32_e64 v94, v192, v193, s[92:93]
	v_lshlrev_b64 v[92:93], 12, v[92:93]
	v_pk_fma_f32 v[28:29], v[188:189], v[150:151], v[28:29]
	v_lshl_add_u64 v[94:95], v[94:95], 0, v[92:93]
	v_add_f32_e32 v188, v28, v29
	v_lshl_add_u64 v[94:95], v[94:95], 0, s[36:37]
	ds_bpermute_b32 v189, v187, v188
	v_lshl_add_u64 v[28:29], v[94:95], 0, v[98:99]
	s_waitcnt vmcnt(20)
	v_mov_b32_e32 v94, v89
	v_mov_b32_e32 v89, v91
	v_mov_b32_e32 v95, v90
	v_pk_mul_f32 v[88:89], v[88:89], v[152:153]
	s_waitcnt lgkmcnt(0)
	v_add_f32_e32 v188, v188, v189
	v_pk_fma_f32 v[88:89], v[94:95], v[150:151], v[88:89]
	ds_bpermute_b32 v189, v186, v188
	v_add_f32_e32 v89, v88, v89
	ds_bpermute_b32 v90, v187, v89
	ds_bpermute_b32 v191, v185, v190
	v_cndmask_b32_e64 v1, 0, v1, s[90:91]
	s_waitcnt lgkmcnt(2)
	v_add_f32_e32 v91, v188, v189
	ds_bpermute_b32 v94, v185, v91
	s_waitcnt lgkmcnt(2)
	v_add_f32_e32 v89, v89, v90
	ds_bpermute_b32 v90, v186, v89
	s_waitcnt lgkmcnt(2)
	v_add_f32_e32 v190, v190, v191
	ds_bpermute_b32 v191, v184, v190
	s_waitcnt lgkmcnt(2)
	v_add_f32_e32 v94, v91, v94
	s_waitcnt vmcnt(19)
	v_mov_b32_e32 v91, v86
	s_waitcnt lgkmcnt(1)
	v_add_f32_e32 v89, v89, v90
	v_mov_b32_e32 v90, v85
	v_mov_b32_e32 v85, v87
	v_pk_mul_f32 v[84:85], v[84:85], v[152:153]
	s_waitcnt vmcnt(18)
	v_mov_b32_e32 v87, v82
	v_pk_fma_f32 v[84:85], v[90:91], v[150:151], v[84:85]
	ds_bpermute_b32 v189, v185, v89
	v_add_f32_e32 v85, v84, v85
	ds_bpermute_b32 v86, v187, v85
	ds_bpermute_b32 v188, v184, v94
	s_waitcnt lgkmcnt(3)
	v_add_f32_e32 v88, v190, v191
	s_waitcnt lgkmcnt(2)
	v_add_f32_e32 v89, v89, v189
	ds_bpermute_b32 v90, v184, v89
	s_waitcnt lgkmcnt(2)
	v_add_f32_e32 v85, v85, v86
	v_mov_b32_e32 v86, v81
	v_mov_b32_e32 v81, v83
	v_pk_mul_f32 v[80:81], v[80:81], v[152:153]
	ds_bpermute_b32 v91, v186, v85
	v_pk_fma_f32 v[80:81], v[86:87], v[150:151], v[80:81]
	s_waitcnt lgkmcnt(1)
	v_add_f32_e32 v82, v89, v90
	v_add_f32_e32 v80, v80, v81
	ds_bpermute_b32 v81, v187, v80
	s_waitcnt lgkmcnt(1)
	v_add_f32_e32 v83, v85, v91
	ds_bpermute_b32 v85, v185, v83
	v_mul_f32_e32 v88, 0x3e000000, v88
	v_add_f32_e32 v84, v94, v188
	s_waitcnt lgkmcnt(1)
	v_add_f32_e32 v81, v80, v81
	ds_bpermute_b32 v87, v186, v81
	v_mul_f32_e32 v80, 0x3e000000, v82
	s_waitcnt vmcnt(17)
	v_mov_b32_e32 v82, v77
	v_mov_b32_e32 v77, v79
	s_waitcnt lgkmcnt(1)
	v_add_f32_e32 v85, v83, v85
	s_waitcnt lgkmcnt(0)
	v_add_f32_e32 v81, v81, v87
	ds_bpermute_b32 v87, v185, v81
	v_mov_b32_e32 v83, v78
	v_pk_mul_f32 v[76:77], v[76:77], v[152:153]
	ds_bpermute_b32 v90, v184, v85
	v_pk_fma_f32 v[76:77], v[82:83], v[150:151], v[76:77]
	s_waitcnt lgkmcnt(1)
	v_add_f32_e32 v79, v81, v87
	v_add_f32_e32 v76, v76, v77
	ds_bpermute_b32 v77, v187, v76
	ds_bpermute_b32 v81, v184, v79
	s_waitcnt lgkmcnt(2)
	v_add_f32_e32 v78, v85, v90
	v_mul_f32_e32 v95, 0x3fb8aa3b, v88
	v_mul_f32_e32 v84, 0x3e000000, v84
	s_waitcnt lgkmcnt(1)
	v_add_f32_e32 v83, v76, v77
	v_mul_f32_e32 v76, 0x3e000000, v78
	s_waitcnt vmcnt(16)
	v_mov_b32_e32 v78, v73
	v_mov_b32_e32 v73, v75
	s_waitcnt lgkmcnt(0)
	v_add_f32_e32 v77, v79, v81
	v_mov_b32_e32 v79, v74
	v_pk_mul_f32 v[72:73], v[72:73], v[152:153]
	ds_bpermute_b32 v85, v186, v83
	v_pk_fma_f32 v[72:73], v[78:79], v[150:151], v[72:73]
	v_max_f32_e32 v95, 0xff800000, v95
	v_add_f32_e32 v72, v72, v73
	ds_bpermute_b32 v73, v187, v72
	s_waitcnt lgkmcnt(1)
	v_add_f32_e32 v81, v83, v85
	ds_bpermute_b32 v83, v185, v81
	v_mul_f32_e32 v86, 0x3fb8aa3b, v84
	v_mul_f32_e32 v89, 0x3fb8aa3b, v80
	s_waitcnt lgkmcnt(1)
	v_add_f32_e32 v79, v72, v73
	s_waitcnt vmcnt(15)
	v_mov_b32_e32 v72, v69
	v_mov_b32_e32 v69, v71
	v_mov_b32_e32 v73, v70
	v_pk_mul_f32 v[68:69], v[68:69], v[152:153]
	s_waitcnt lgkmcnt(0)
	v_add_f32_e32 v75, v81, v83
	v_pk_fma_f32 v[68:69], v[72:73], v[150:151], v[68:69]
	ds_bpermute_b32 v81, v186, v79
	v_add_f32_e32 v68, v68, v69
	ds_bpermute_b32 v69, v187, v68
	ds_bpermute_b32 v78, v184, v75
	v_mul_f32_e32 v77, 0x3e000000, v77
	s_waitcnt lgkmcnt(2)
	v_add_f32_e32 v71, v79, v81
	ds_bpermute_b32 v72, v185, v71
	s_waitcnt lgkmcnt(2)
	v_add_f32_e32 v73, v68, v69
	s_waitcnt vmcnt(14)
	v_mov_b32_e32 v68, v65
	v_mov_b32_e32 v65, v67
	v_mov_b32_e32 v69, v66
	v_pk_mul_f32 v[64:65], v[64:65], v[152:153]
	s_waitcnt lgkmcnt(1)
	v_add_f32_e32 v70, v75, v78
	v_pk_fma_f32 v[64:65], v[68:69], v[150:151], v[64:65]
	ds_bpermute_b32 v75, v186, v73
	v_add_f32_e32 v64, v64, v65
	ds_bpermute_b32 v65, v187, v64
	s_waitcnt lgkmcnt(2)
	v_add_f32_e32 v66, v71, v72
	ds_bpermute_b32 v67, v184, v66
	s_waitcnt lgkmcnt(2)
	v_add_f32_e32 v68, v73, v75
	ds_bpermute_b32 v69, v185, v68
	s_waitcnt lgkmcnt(2)
	v_add_f32_e32 v64, v64, v65
	ds_bpermute_b32 v65, v186, v64
	s_waitcnt lgkmcnt(2)
	v_add_f32_e32 v66, v66, v67
	v_max3_f32 v82, v95, v86, v89
	s_waitcnt lgkmcnt(1)
	v_add_f32_e32 v67, v68, v69
	ds_bpermute_b32 v68, v184, v67
	s_waitcnt lgkmcnt(1)
	v_add_f32_e32 v64, v64, v65
	ds_bpermute_b32 v65, v185, v64
	v_mul_f32_e32 v86, 0x3fb8aa3b, v76
	v_mul_f32_e32 v74, 0x3fb8aa3b, v77
	s_waitcnt lgkmcnt(1)
	v_add_f32_e32 v67, v67, v68
	v_mul_f32_e32 v70, 0x3e000000, v70
	s_waitcnt lgkmcnt(0)
	v_add_f32_e32 v68, v64, v65
	s_waitcnt vmcnt(13)
	v_mov_b32_e32 v64, v61
	v_mov_b32_e32 v61, v63
	v_mov_b32_e32 v65, v62
	v_pk_mul_f32 v[60:61], v[60:61], v[152:153]
	v_mul_f32_e32 v66, 0x3e000000, v66
	v_pk_fma_f32 v[60:61], v[64:65], v[150:151], v[60:61]
	v_max3_f32 v74, v82, v86, v74
	v_add_f32_e32 v60, v60, v61
	ds_bpermute_b32 v61, v187, v60
	v_mul_f32_e32 v71, 0x3fb8aa3b, v70
	v_mul_f32_e32 v69, 0x3fb8aa3b, v66
	v_max3_f32 v69, v74, v71, v69
	ds_bpermute_b32 v71, v184, v68
	s_waitcnt lgkmcnt(1)
	v_add_f32_e32 v65, v60, v61
	s_waitcnt vmcnt(12)
	v_mov_b32_e32 v60, v57
	v_mov_b32_e32 v57, v59
	v_mov_b32_e32 v61, v58
	v_pk_mul_f32 v[56:57], v[56:57], v[152:153]
	v_mul_f32_e32 v62, 0x3e000000, v67
	v_pk_fma_f32 v[56:57], v[60:61], v[150:151], v[56:57]
	ds_bpermute_b32 v67, v186, v65
	v_add_f32_e32 v56, v56, v57
	ds_bpermute_b32 v57, v187, v56
	s_waitcnt lgkmcnt(2)
	v_add_f32_e32 v64, v68, v71
	v_mul_f32_e32 v64, 0x3e000000, v64
	v_mul_f32_e32 v63, 0x3fb8aa3b, v62
	v_mul_f32_e32 v58, 0x3fb8aa3b, v64
	s_waitcnt lgkmcnt(0)
	v_add_f32_e32 v61, v56, v57
	s_waitcnt vmcnt(11)
	v_mov_b32_e32 v56, v53
	v_mov_b32_e32 v53, v55
	v_mov_b32_e32 v57, v54
	v_pk_mul_f32 v[52:53], v[52:53], v[152:153]
	v_add_f32_e32 v59, v65, v67
	v_pk_fma_f32 v[52:53], v[56:57], v[150:151], v[52:53]
	v_max3_f32 v58, v69, v63, v58
	v_add_f32_e32 v52, v52, v53
	ds_bpermute_b32 v60, v185, v59
	ds_bpermute_b32 v63, v186, v61
	ds_bpermute_b32 v53, v187, v52
	v_cndmask_b32_e64 v2, v192, v193, s[90:91]
	v_lshlrev_b64 v[148:149], 12, v[0:1]
	s_waitcnt lgkmcnt(2)
	v_add_f32_e32 v54, v59, v60
	s_waitcnt lgkmcnt(1)
	v_add_f32_e32 v56, v61, v63
	s_waitcnt lgkmcnt(0)
	v_add_f32_e32 v52, v52, v53
	ds_bpermute_b32 v55, v184, v54
	ds_bpermute_b32 v57, v185, v56
	ds_bpermute_b32 v53, v186, v52
	v_lshl_add_u64 v[0:1], v[2:3], 0, v[148:149]
	v_lshl_add_u64 v[0:1], v[0:1], 0, s[36:37]
	s_waitcnt lgkmcnt(2)
	v_add_f32_e32 v54, v54, v55
	s_waitcnt lgkmcnt(1)
	v_add_f32_e32 v55, v56, v57
	s_waitcnt lgkmcnt(0)
	v_add_f32_e32 v57, v52, v53
	s_waitcnt vmcnt(10)
	v_mov_b32_e32 v52, v49
	v_mov_b32_e32 v49, v51
	v_mov_b32_e32 v53, v50
	v_pk_mul_f32 v[48:49], v[48:49], v[152:153]
	ds_bpermute_b32 v59, v185, v57
	v_pk_fma_f32 v[48:49], v[52:53], v[150:151], v[48:49]
	ds_bpermute_b32 v56, v184, v55
	v_add_f32_e32 v48, v48, v49
	ds_bpermute_b32 v49, v187, v48
	s_waitcnt lgkmcnt(2)
	v_add_f32_e32 v52, v57, v59
	ds_bpermute_b32 v53, v184, v52
	s_waitcnt lgkmcnt(2)
	v_add_f32_e32 v51, v55, v56
	v_mul_f32_e32 v54, 0x3e000000, v54
	s_waitcnt lgkmcnt(1)
	v_add_f32_e32 v48, v48, v49
	ds_bpermute_b32 v49, v186, v48
	s_waitcnt lgkmcnt(1)
	v_add_f32_e32 v52, v52, v53
	v_mul_f32_e32 v51, 0x3e000000, v51
	v_mul_f32_e32 v50, 0x3fb8aa3b, v54
	v_mul_f32_e32 v55, 0x3fb8aa3b, v51
	s_waitcnt lgkmcnt(0)
	v_add_f32_e32 v53, v48, v49
	s_waitcnt vmcnt(9)
	v_mov_b32_e32 v48, v45
	v_mov_b32_e32 v45, v47
	v_mov_b32_e32 v49, v46
	v_pk_mul_f32 v[44:45], v[44:45], v[152:153]
	v_mul_f32_e32 v47, 0x3e000000, v52
	v_pk_fma_f32 v[44:45], v[48:49], v[150:151], v[44:45]
	v_max3_f32 v50, v58, v50, v55
	v_add_f32_e32 v44, v44, v45
	ds_bpermute_b32 v45, v187, v44
	ds_bpermute_b32 v55, v185, v53
	v_mul_f32_e32 v46, 0x3fb8aa3b, v47
	v_lshl_add_u64 v[0:1], v[0:1], 0, v[98:99]
	global_load_dwordx4 v[0:3], v[0:1], off
	s_waitcnt lgkmcnt(1)
	v_add_f32_e32 v52, v44, v45
	s_waitcnt vmcnt(9)
	v_mov_b32_e32 v44, v41
	v_mov_b32_e32 v41, v43
	v_mov_b32_e32 v45, v42
	v_pk_mul_f32 v[40:41], v[40:41], v[152:153]
	s_waitcnt lgkmcnt(0)
	v_add_f32_e32 v48, v53, v55
	v_pk_fma_f32 v[40:41], v[44:45], v[150:151], v[40:41]
	ds_bpermute_b32 v49, v184, v48
	v_add_f32_e32 v40, v40, v41
	ds_bpermute_b32 v41, v187, v40
	ds_bpermute_b32 v53, v186, v52
	global_load_dwordx4 v[28:31], v[28:29], off
	s_waitcnt lgkmcnt(2)
	v_add_f32_e32 v42, v48, v49
	v_mul_f32_e32 v45, 0x3e000000, v42
	s_waitcnt lgkmcnt(1)
	v_add_f32_e32 v40, v40, v41
	ds_bpermute_b32 v41, v186, v40
	v_mul_f32_e32 v44, 0x3fb8aa3b, v45
	v_max3_f32 v44, v50, v46, v44
	s_waitcnt lgkmcnt(1)
	v_add_f32_e32 v42, v52, v53
	ds_bpermute_b32 v43, v185, v42
	s_waitcnt lgkmcnt(1)
	v_add_f32_e32 v46, v40, v41
	s_waitcnt vmcnt(9)
	v_mov_b32_e32 v40, v37
	v_mov_b32_e32 v37, v39
	v_mov_b32_e32 v41, v38
	v_pk_mul_f32 v[36:37], v[36:37], v[152:153]
	s_waitcnt vmcnt(8)
	v_mov_b32_e32 v39, v34
	v_pk_fma_f32 v[36:37], v[40:41], v[150:151], v[36:37]
	ds_bpermute_b32 v48, v185, v46
	v_add_f32_e32 v36, v36, v37
	ds_bpermute_b32 v38, v187, v36
	s_waitcnt lgkmcnt(2)
	v_add_f32_e32 v42, v42, v43
	ds_bpermute_b32 v43, v184, v42
	s_waitcnt lgkmcnt(2)
	v_add_f32_e32 v40, v46, v48
	ds_bpermute_b32 v41, v184, v40
	s_waitcnt lgkmcnt(2)
	v_add_f32_e32 v36, v36, v38
	v_mov_b32_e32 v38, v33
	v_mov_b32_e32 v33, v35
	v_pk_mul_f32 v[32:33], v[32:33], v[152:153]
	s_waitcnt lgkmcnt(1)
	v_add_f32_e32 v37, v42, v43
	v_pk_fma_f32 v[32:33], v[38:39], v[150:151], v[32:33]
	s_waitcnt lgkmcnt(0)
	v_add_f32_e32 v38, v40, v41
	v_add_f32_e32 v32, v32, v33
	ds_bpermute_b32 v33, v187, v32
	v_mul_f32_e32 v37, 0x3e000000, v37
	v_mul_f32_e32 v34, 0x3fb8aa3b, v37
	ds_bpermute_b32 v42, v186, v36
	s_waitcnt lgkmcnt(1)
	v_add_f32_e32 v32, v32, v33
	ds_bpermute_b32 v39, v186, v32
	v_mul_f32_e32 v33, 0x3e000000, v38
	v_mul_f32_e32 v38, 0x3fb8aa3b, v33
	v_max3_f32 v34, v44, v34, v38
	s_waitcnt vmcnt(7)
	v_mov_b32_e32 v38, v21
	s_waitcnt lgkmcnt(0)
	v_add_f32_e32 v32, v32, v39
	ds_bpermute_b32 v39, v185, v32
	v_mov_b32_e32 v21, v23
	v_pk_mul_f32 v[20:21], v[20:21], v[152:153]
	v_add_f32_e32 v35, v36, v42
	ds_bpermute_b32 v36, v185, v35
	s_waitcnt lgkmcnt(1)
	v_add_f32_e32 v32, v32, v39
	v_mov_b32_e32 v39, v22
	v_pk_fma_f32 v[20:21], v[38:39], v[150:151], v[20:21]
	ds_bpermute_b32 v40, v184, v32
	v_add_f32_e32 v38, v20, v21
	s_waitcnt vmcnt(6)
	v_mov_b32_e32 v20, v25
	v_mov_b32_e32 v25, v27
	v_mov_b32_e32 v21, v26
	v_pk_mul_f32 v[22:23], v[24:25], v[152:153]
	ds_bpermute_b32 v41, v187, v38
	v_pk_fma_f32 v[20:21], v[20:21], v[150:151], v[22:23]
	s_waitcnt lgkmcnt(1)
	v_add_f32_e32 v22, v32, v40
	v_add_f32_e32 v20, v20, v21
	ds_bpermute_b32 v21, v187, v20
	v_mul_f32_e32 v39, 0x3e000000, v22
	s_waitcnt lgkmcnt(1)
	v_add_f32_e32 v22, v38, v41
	ds_bpermute_b32 v23, v186, v22
	v_add_f32_e32 v35, v35, v36
	s_waitcnt lgkmcnt(1)
	v_add_f32_e32 v20, v20, v21
	ds_bpermute_b32 v21, v186, v20
	ds_bpermute_b32 v36, v184, v35
	s_waitcnt lgkmcnt(2)
	v_add_f32_e32 v22, v22, v23
	ds_bpermute_b32 v23, v185, v22
	v_mul_f32_e32 v24, 0x3fb8aa3b, v39
	s_waitcnt lgkmcnt(2)
	v_add_f32_e32 v25, v20, v21
	s_waitcnt vmcnt(5)
	v_mov_b32_e32 v20, v17
	v_mov_b32_e32 v17, v19
	v_mov_b32_e32 v21, v18
	v_pk_mul_f32 v[16:17], v[16:17], v[152:153]
	ds_bpermute_b32 v26, v185, v25
	v_pk_fma_f32 v[16:17], v[20:21], v[150:151], v[16:17]
	s_waitcnt lgkmcnt(1)
	v_add_f32_e32 v18, v22, v23
	v_add_f32_e32 v16, v16, v17
	ds_bpermute_b32 v17, v187, v16
	s_waitcnt lgkmcnt(1)
	v_add_f32_e32 v20, v25, v26
	ds_bpermute_b32 v19, v184, v18
	ds_bpermute_b32 v21, v184, v20
	v_add_f32_e32 v35, v35, v36
	s_waitcnt lgkmcnt(2)
	v_add_f32_e32 v16, v16, v17
	ds_bpermute_b32 v17, v186, v16
	s_waitcnt lgkmcnt(2)
	v_add_f32_e32 v18, v18, v19
	s_waitcnt lgkmcnt(1)
	v_add_f32_e32 v19, v20, v21
	v_mul_f32_e32 v43, 0x3e000000, v19
	v_mul_f32_e32 v35, 0x3e000000, v35
	s_waitcnt lgkmcnt(0)
	v_add_f32_e32 v20, v16, v17
	s_waitcnt vmcnt(4)
	v_mov_b32_e32 v16, v13
	v_mov_b32_e32 v13, v15
	v_mov_b32_e32 v17, v14
	v_pk_mul_f32 v[12:13], v[12:13], v[152:153]
	ds_bpermute_b32 v21, v185, v20
	v_pk_fma_f32 v[12:13], v[16:17], v[150:151], v[12:13]
	v_mul_f32_e32 v36, 0x3fb8aa3b, v35
	v_add_f32_e32 v12, v12, v13
	ds_bpermute_b32 v13, v187, v12
	s_waitcnt lgkmcnt(1)
	v_add_f32_e32 v15, v20, v21
	v_mul_f32_e32 v41, 0x3e000000, v18
	ds_bpermute_b32 v16, v184, v15
	v_max3_f32 v24, v34, v36, v24
	s_waitcnt lgkmcnt(1)
	v_add_f32_e32 v17, v12, v13
	s_waitcnt vmcnt(3)
	v_mov_b32_e32 v12, v9
	v_mov_b32_e32 v9, v11
	v_mov_b32_e32 v13, v10
	v_pk_mul_f32 v[8:9], v[8:9], v[152:153]
	ds_bpermute_b32 v19, v186, v17
	v_pk_fma_f32 v[8:9], v[12:13], v[150:151], v[8:9]
	v_mul_f32_e32 v18, 0x3fb8aa3b, v41
	v_add_f32_e32 v8, v8, v9
	ds_bpermute_b32 v9, v187, v8
	s_waitcnt lgkmcnt(1)
	v_add_f32_e32 v12, v17, v19
	ds_bpermute_b32 v13, v185, v12
	v_mul_f32_e32 v14, 0x3fb8aa3b, v43
	v_max3_f32 v10, v24, v18, v14
	s_waitcnt lgkmcnt(1)
	v_add_f32_e32 v8, v8, v9
	ds_bpermute_b32 v9, v186, v8
	s_waitcnt lgkmcnt(1)
	v_add_f32_e32 v12, v12, v13
	ds_bpermute_b32 v13, v184, v12
	v_add_f32_e32 v11, v15, v16
	v_mul_f32_e32 v49, 0x3e000000, v11
	s_waitcnt lgkmcnt(1)
	v_add_f32_e32 v14, v8, v9
	s_waitcnt vmcnt(2)
	v_mov_b32_e32 v8, v5
	v_mov_b32_e32 v5, v7
	v_mov_b32_e32 v9, v6
	v_pk_mul_f32 v[4:5], v[4:5], v[152:153]
	ds_bpermute_b32 v15, v185, v14
	v_pk_fma_f32 v[4:5], v[8:9], v[150:151], v[4:5]
	s_waitcnt lgkmcnt(1)
	v_add_f32_e32 v6, v12, v13
	v_add_f32_e32 v4, v4, v5
	ds_bpermute_b32 v5, v187, v4
	v_mul_f32_e32 v53, 0x3e000000, v6
	s_waitcnt lgkmcnt(1)
	v_add_f32_e32 v6, v14, v15
	ds_bpermute_b32 v7, v184, v6
	v_mul_f32_e32 v11, 0x3fb8aa3b, v49
	s_waitcnt lgkmcnt(1)
	v_add_f32_e32 v4, v4, v5
	ds_bpermute_b32 v5, v186, v4
	v_mul_f32_e32 v8, 0x3fb8aa3b, v53
	s_waitcnt lgkmcnt(1)
	v_add_f32_e32 v6, v6, v7
	v_mul_f32_e32 v55, 0x3e000000, v6
	v_max3_f32 v8, v10, v11, v8
	s_waitcnt lgkmcnt(0)
	v_add_f32_e32 v6, v4, v5
	s_waitcnt vmcnt(1)
	v_mov_b32_e32 v4, v1
	v_mov_b32_e32 v1, v3
	v_mov_b32_e32 v5, v2
	v_pk_mul_f32 v[0:1], v[0:1], v[152:153]
	ds_bpermute_b32 v7, v185, v6
	v_pk_fma_f32 v[0:1], v[4:5], v[150:151], v[0:1]
	s_nop 0
	v_add_f32_e32 v4, v0, v1
	s_waitcnt vmcnt(0)
	v_mov_b32_e32 v0, v29
	v_mov_b32_e32 v29, v31
	v_mov_b32_e32 v1, v30
	v_pk_mul_f32 v[2:3], v[28:29], v[152:153]
	ds_bpermute_b32 v5, v187, v4
	v_pk_fma_f32 v[0:1], v[0:1], v[150:151], v[2:3]
	s_waitcnt lgkmcnt(1)
	v_add_f32_e32 v2, v6, v7
	v_add_f32_e32 v0, v0, v1
	ds_bpermute_b32 v1, v187, v0
	s_waitcnt lgkmcnt(1)
	v_add_f32_e32 v3, v4, v5
	ds_bpermute_b32 v4, v186, v3
	ds_bpermute_b32 v5, v184, v2
	v_mul_f32_e32 v6, 0x3fb8aa3b, v55
	s_waitcnt lgkmcnt(2)
	v_add_f32_e32 v0, v0, v1
	ds_bpermute_b32 v1, v186, v0
	s_waitcnt lgkmcnt(2)
	v_add_f32_e32 v3, v3, v4
	ds_bpermute_b32 v4, v185, v3
	s_waitcnt lgkmcnt(2)
	v_add_f32_e32 v2, v2, v5
	v_mul_f32_e32 v57, 0x3e000000, v2
	s_waitcnt lgkmcnt(1)
	v_add_f32_e32 v0, v0, v1
	ds_bpermute_b32 v1, v185, v0
	s_waitcnt lgkmcnt(1)
	v_add_f32_e32 v2, v3, v4
	ds_bpermute_b32 v3, v184, v2
	v_mul_f32_e32 v4, 0x3fb8aa3b, v57
	v_max3_f32 v4, v8, v6, v4
	s_waitcnt lgkmcnt(1)
	v_add_f32_e32 v0, v0, v1
	ds_bpermute_b32 v1, v184, v0
	s_waitcnt lgkmcnt(1)
	v_add_f32_e32 v2, v2, v3
	v_mul_f32_e32 v59, 0x3e000000, v2
	v_mul_f32_e32 v2, 0x3fb8aa3b, v59
	v_mov_b32_e32 v150, s0
	s_waitcnt lgkmcnt(0)
	v_add_f32_e32 v0, v0, v1
	v_mul_f32_e32 v0, 0x3e000000, v0
	v_xor_b32_e32 v1, 16, v182
	v_mul_f32_e32 v0, 0x3fb8aa3b, v0
	v_cmp_lt_i32_e64 s[94:95], v1, v101
	v_cndmask_b32_e64 v151, v183, v0, s[40:41]
	v_max3_f32 v0, v4, v2, v151
	v_cndmask_b32_e64 v1, v182, v1, s[94:95]
	v_lshlrev_b32_e32 v153, 2, v1
	ds_bpermute_b32 v1, v153, v0
	v_mov_b32_e32 v152, s50
	v_cndmask_b32_e64 v94, v150, v152, s[68:69]
	v_cndmask_b32_e64 v4, v150, v152, s[54:55]
	v_cndmask_b32_e64 v8, v150, v152, s[56:57]
	s_waitcnt lgkmcnt(0)
	v_max_f32_e32 v1, v1, v1
	v_max_f32_e32 v0, v0, v1
	v_xor_b32_e32 v1, 32, v182
	v_cmp_lt_i32_e64 s[94:95], v1, v101
	v_cndmask_b32_e64 v20, v150, v152, s[58:59]
	v_cndmask_b32_e64 v12, v150, v152, s[96:97]
	v_cndmask_b32_e64 v1, v182, v1, s[94:95]
	v_lshlrev_b32_e32 v101, 2, v1
	ds_bpermute_b32 v1, v101, v0
	v_cndmask_b32_e64 v24, v150, v152, s[98:99]
	v_cndmask_b32_e64 v16, v150, v152, s[8:9]
	v_cndmask_b32_e64 v28, v150, v152, s[6:7]
	v_cndmask_b32_e64 v60, v150, v152, s[60:61]
	s_waitcnt lgkmcnt(0)
	v_max_f32_e32 v1, v1, v1
	v_max_f32_e32 v32, v0, v1
	v_fma_f32 v0, v88, s15, -v32
	v_exp_f32_e32 v34, v0
	v_fma_f32 v0, v84, s15, -v32
	v_exp_f32_e32 v38, v0
	v_fma_f32 v0, v80, s15, -v32
	v_exp_f32_e32 v42, v0
	v_fma_f32 v1, v76, s15, -v32
	v_exp_f32_e32 v44, v1
	v_fma_f32 v1, v77, s15, -v32
	v_add_f32_e32 v0, 0, v34
	v_exp_f32_e32 v48, v1
	v_fma_f32 v1, v70, s15, -v32
	v_add_f32_e32 v0, v38, v0
	v_exp_f32_e32 v36, v1
	v_fma_f32 v1, v66, s15, -v32
	v_add_f32_e32 v0, v42, v0
	v_exp_f32_e32 v40, v1
	v_fma_f32 v1, v62, s15, -v32
	v_add_f32_e32 v0, v44, v0
	v_exp_f32_e32 v46, v1
	v_fma_f32 v1, v64, s15, -v32
	v_add_f32_e32 v0, v48, v0
	v_exp_f32_e32 v50, v1
	v_fma_f32 v1, v54, s15, -v32
	v_add_f32_e32 v0, v36, v0
	v_exp_f32_e32 v52, v1
	v_fma_f32 v1, v51, s15, -v32
	v_add_f32_e32 v0, v40, v0
	v_exp_f32_e32 v54, v1
	v_add_f32_e32 v0, v46, v0
	v_add_f32_e32 v0, v50, v0
	v_add_f32_e32 v0, v52, v0
	v_add_f32_e32 v51, v54, v0
	v_fma_f32 v0, v47, s15, -v32
	v_exp_f32_e32 v56, v0
	v_fma_f32 v0, v45, s15, -v32
	v_mov_b32_e32 v45, s1
	v_mov_b32_e32 v47, s51
	v_cndmask_b32_e64 v95, v45, v47, s[68:69]
	v_lshl_add_u64 v[94:95], v[94:95], 0, v[126:127]
	v_lshl_add_u64 v[94:95], v[94:95], 0, s[36:37]
	v_exp_f32_e32 v58, v0
	v_cndmask_b32_e64 v1, v45, v47, s[4:5]
	v_cndmask_b32_e64 v0, v150, v152, s[4:5]
	v_cndmask_b32_e64 v5, v45, v47, s[54:55]
	v_lshl_add_u64 v[94:95], v[94:95], 0, v[98:99]
	v_lshl_add_u64 v[0:1], v[0:1], 0, v[102:103]
	v_lshl_add_u64 v[4:5], v[4:5], 0, v[104:105]
	global_load_dwordx4 v[102:105], v[94:95], off
	v_cndmask_b32_e64 v95, v45, v47, s[72:73]
	v_cndmask_b32_e64 v94, v150, v152, s[72:73]
	v_lshl_add_u64 v[94:95], v[94:95], 0, v[130:131]
	v_lshl_add_u64 v[94:95], v[94:95], 0, s[36:37]
	v_cndmask_b32_e64 v9, v45, v47, s[56:57]
	v_cndmask_b32_e64 v21, v45, v47, s[58:59]
	v_lshl_add_u64 v[94:95], v[94:95], 0, v[98:99]
	v_lshl_add_u64 v[8:9], v[8:9], 0, v[106:107]
	v_lshl_add_u64 v[20:21], v[20:21], 0, v[108:109]
	global_load_dwordx4 v[106:109], v[94:95], off
	v_cndmask_b32_e64 v95, v45, v47, s[76:77]
	v_cndmask_b32_e64 v94, v150, v152, s[76:77]
	v_lshl_add_u64 v[94:95], v[94:95], 0, v[134:135]
	v_lshl_add_u64 v[0:1], v[0:1], 0, s[36:37]
	v_lshl_add_u64 v[94:95], v[94:95], 0, s[36:37]
	v_lshl_add_u64 v[0:1], v[0:1], 0, v[98:99]
	v_lshl_add_u64 v[4:5], v[4:5], 0, s[36:37]
	v_cndmask_b32_e64 v13, v45, v47, s[96:97]
	v_cndmask_b32_e64 v25, v45, v47, s[98:99]
	v_lshl_add_u64 v[94:95], v[94:95], 0, v[98:99]
	global_load_dwordx4 v[0:3], v[0:1], off
	v_lshl_add_u64 v[4:5], v[4:5], 0, v[98:99]
	v_lshl_add_u64 v[8:9], v[8:9], 0, s[36:37]
	v_lshl_add_u64 v[12:13], v[12:13], 0, v[110:111]
	v_cndmask_b32_e64 v17, v45, v47, s[8:9]
	v_lshl_add_u64 v[24:25], v[24:25], 0, v[112:113]
	global_load_dwordx4 v[110:113], v[94:95], off
	v_cndmask_b32_e64 v95, v45, v47, s[80:81]
	v_cndmask_b32_e64 v94, v150, v152, s[80:81]
	global_load_dwordx4 v[4:7], v[4:5], off
	v_lshl_add_u64 v[8:9], v[8:9], 0, v[98:99]
	v_lshl_add_u64 v[12:13], v[12:13], 0, s[36:37]
	v_lshl_add_u64 v[16:17], v[16:17], 0, v[114:115]
	v_lshl_add_u64 v[94:95], v[94:95], 0, v[138:139]
	global_load_dwordx4 v[8:11], v[8:9], off
	v_lshl_add_u64 v[12:13], v[12:13], 0, v[98:99]
	v_lshl_add_u64 v[16:17], v[16:17], 0, s[36:37]
	v_lshl_add_u64 v[94:95], v[94:95], 0, s[36:37]
	global_load_dwordx4 v[12:15], v[12:13], off
	v_lshl_add_u64 v[16:17], v[16:17], 0, v[98:99]
	v_lshl_add_u64 v[20:21], v[20:21], 0, s[36:37]
	v_cndmask_b32_e64 v29, v45, v47, s[6:7]
	v_lshl_add_u64 v[94:95], v[94:95], 0, v[98:99]
	global_load_dwordx4 v[16:19], v[16:17], off
	v_lshl_add_u64 v[20:21], v[20:21], 0, v[98:99]
	v_lshl_add_u64 v[24:25], v[24:25], 0, s[36:37]
	v_lshl_add_u64 v[28:29], v[28:29], 0, v[116:117]
	v_cndmask_b32_e64 v61, v45, v47, s[60:61]
	global_load_dwordx4 v[114:117], v[94:95], off
	v_cndmask_b32_e64 v95, v45, v47, s[84:85]
	v_cndmask_b32_e64 v94, v150, v152, s[84:85]
	global_load_dwordx4 v[20:23], v[20:21], off
	v_lshl_add_u64 v[24:25], v[24:25], 0, v[98:99]
	v_lshl_add_u64 v[28:29], v[28:29], 0, s[36:37]
	v_lshl_add_u64 v[60:61], v[60:61], 0, v[118:119]
	v_cndmask_b32_e64 v65, v45, v47, s[62:63]
	v_cndmask_b32_e64 v64, v150, v152, s[62:63]
	v_lshl_add_u64 v[94:95], v[94:95], 0, v[142:143]
	global_load_dwordx4 v[24:27], v[24:25], off
	v_lshl_add_u64 v[28:29], v[28:29], 0, v[98:99]
	v_lshl_add_u64 v[60:61], v[60:61], 0, s[36:37]
	v_lshl_add_u64 v[64:65], v[64:65], 0, v[120:121]
	v_cndmask_b32_e32 v69, v45, v47, vcc
	v_cndmask_b32_e32 v68, v150, v152, vcc
	v_lshl_add_u64 v[94:95], v[94:95], 0, s[36:37]
	global_load_dwordx4 v[28:31], v[28:29], off
	v_lshl_add_u64 v[60:61], v[60:61], 0, v[98:99]
	v_lshl_add_u64 v[64:65], v[64:65], 0, s[36:37]
	v_lshl_add_u64 v[68:69], v[68:69], 0, v[122:123]
	v_cndmask_b32_e64 v73, v45, v47, s[10:11]
	v_cndmask_b32_e64 v72, v150, v152, s[10:11]
	v_lshl_add_u64 v[94:95], v[94:95], 0, v[98:99]
	global_load_dwordx4 v[60:63], v[60:61], off
	v_lshl_add_u64 v[64:65], v[64:65], 0, v[98:99]
	v_lshl_add_u64 v[68:69], v[68:69], 0, s[36:37]
	v_lshl_add_u64 v[72:73], v[72:73], 0, v[124:125]
	v_cndmask_b32_e64 v77, v45, v47, s[70:71]
	v_cndmask_b32_e64 v76, v150, v152, s[70:71]
	global_load_dwordx4 v[118:121], v[94:95], off
	v_cndmask_b32_e64 v95, v45, v47, s[86:87]
	v_cndmask_b32_e64 v94, v150, v152, s[86:87]
	global_load_dwordx4 v[64:67], v[64:65], off
	v_lshl_add_u64 v[68:69], v[68:69], 0, v[98:99]
	v_lshl_add_u64 v[72:73], v[72:73], 0, s[36:37]
	v_lshl_add_u64 v[76:77], v[76:77], 0, v[128:129]
	v_cndmask_b32_e64 v81, v45, v47, s[74:75]
	v_cndmask_b32_e64 v80, v150, v152, s[74:75]
	v_lshl_add_u64 v[94:95], v[94:95], 0, v[144:145]
	global_load_dwordx4 v[68:71], v[68:69], off
	v_lshl_add_u64 v[72:73], v[72:73], 0, v[98:99]
	v_lshl_add_u64 v[76:77], v[76:77], 0, s[36:37]
	v_lshl_add_u64 v[80:81], v[80:81], 0, v[132:133]
	v_cndmask_b32_e64 v85, v45, v47, s[78:79]
	v_cndmask_b32_e64 v84, v150, v152, s[78:79]
	v_lshl_add_u64 v[94:95], v[94:95], 0, s[36:37]
	global_load_dwordx4 v[72:75], v[72:73], off
	v_lshl_add_u64 v[76:77], v[76:77], 0, v[98:99]
	v_lshl_add_u64 v[80:81], v[80:81], 0, s[36:37]
	v_lshl_add_u64 v[84:85], v[84:85], 0, v[136:137]
	v_cndmask_b32_e64 v89, v45, v47, s[82:83]
	v_cndmask_b32_e64 v88, v150, v152, s[82:83]
	v_lshl_add_u64 v[94:95], v[94:95], 0, v[98:99]
	global_load_dwordx4 v[76:79], v[76:77], off
	v_lshl_add_u64 v[80:81], v[80:81], 0, v[98:99]
	v_lshl_add_u64 v[84:85], v[84:85], 0, s[36:37]
	v_lshl_add_u64 v[88:89], v[88:89], 0, v[140:141]
	global_load_dwordx4 v[122:125], v[94:95], off
	v_cndmask_b32_e64 v95, v45, v47, s[88:89]
	v_cndmask_b32_e64 v94, v150, v152, s[88:89]
	global_load_dwordx4 v[80:83], v[80:81], off
	v_lshl_add_u64 v[84:85], v[84:85], 0, v[98:99]
	v_lshl_add_u64 v[88:89], v[88:89], 0, s[36:37]
	v_lshl_add_u64 v[94:95], v[94:95], 0, v[146:147]
	global_load_dwordx4 v[84:87], v[84:85], off
	v_lshl_add_u64 v[88:89], v[88:89], 0, v[98:99]
	v_lshl_add_u64 v[94:95], v[94:95], 0, s[36:37]
	global_load_dwordx4 v[88:91], v[88:89], off
	v_lshl_add_u64 v[94:95], v[94:95], 0, v[98:99]
	global_load_dwordx4 v[126:129], v[94:95], off
	v_cndmask_b32_e64 v95, v45, v47, s[90:91]
	v_cndmask_b32_e64 v94, v150, v152, s[90:91]
	v_lshl_add_u64 v[94:95], v[94:95], 0, v[148:149]
	v_lshl_add_u64 v[94:95], v[94:95], 0, s[36:37]
	v_lshl_add_u64 v[94:95], v[94:95], 0, v[98:99]
	global_load_dwordx4 v[130:133], v[94:95], off
	v_cndmask_b32_e64 v95, v45, v47, s[92:93]
	v_cndmask_b32_e64 v94, v150, v152, s[92:93]
	v_lshl_add_u64 v[92:93], v[94:95], 0, v[92:93]
	v_lshl_add_u64 v[92:93], v[92:93], 0, s[36:37]
	v_lshl_add_u64 v[92:93], v[92:93], 0, v[98:99]
	global_load_dwordx4 v[92:95], v[92:93], off
	v_fma_f32 v37, v37, s15, -v32
	v_exp_f32_e32 v98, v37
	v_fma_f32 v33, v33, s15, -v32
	v_exp_f32_e32 v134, v33
	v_fma_f32 v33, v35, s15, -v32
	v_add_f32_e32 v45, v56, v51
	v_exp_f32_e32 v136, v33
	v_fma_f32 v33, v39, s15, -v32
	v_add_f32_e32 v45, v58, v45
	v_exp_f32_e32 v138, v33
	v_fma_f32 v35, v41, s15, -v32
	v_add_f32_e32 v33, v98, v45
	v_exp_f32_e32 v140, v35
	v_fma_f32 v35, v43, s15, -v32
	v_add_f32_e32 v33, v134, v33
	v_exp_f32_e32 v142, v35
	v_fma_f32 v35, v49, s15, -v32
	v_add_f32_e32 v33, v136, v33
	v_exp_f32_e32 v144, v35
	v_fma_f32 v35, v53, s15, -v32
	v_add_f32_e32 v33, v138, v33
	v_exp_f32_e32 v146, v35
	v_fma_f32 v35, v55, s15, -v32
	v_add_f32_e32 v33, v140, v33
	v_exp_f32_e32 v148, v35
	v_fma_f32 v35, v57, s15, -v32
	v_add_f32_e32 v33, v142, v33
	v_exp_f32_e32 v150, v35
	v_fma_f32 v35, v59, s15, -v32
	v_add_f32_e32 v33, v144, v33
	v_exp_f32_e32 v152, v35
	v_sub_f32_e32 v35, v151, v32
	v_add_f32_e32 v33, v146, v33
	v_exp_f32_e32 v184, v35
	v_add_f32_e32 v33, v148, v33
	v_add_f32_e32 v33, v150, v33
	v_add_f32_e32 v33, v152, v33
	v_add_f32_e32 v33, v184, v33
	ds_bpermute_b32 v35, v153, v33
	s_waitcnt vmcnt(22) lgkmcnt(0)
	v_pk_fma_f32 v[0:1], v[0:1], v[34:35], 0 op_sel_hi:[1,0,0]
	v_pk_fma_f32 v[2:3], v[2:3], v[34:35], 0 op_sel_hi:[1,0,0]
	s_waitcnt vmcnt(20)
	v_pk_fma_f32 v[0:1], v[4:5], v[38:39], v[0:1] op_sel_hi:[1,0,1]
	v_pk_fma_f32 v[2:3], v[6:7], v[38:39], v[2:3] op_sel_hi:[1,0,1]
	s_waitcnt vmcnt(19)
	v_pk_fma_f32 v[0:1], v[8:9], v[42:43], v[0:1] op_sel_hi:[1,0,1]
	v_pk_fma_f32 v[2:3], v[10:11], v[42:43], v[2:3] op_sel_hi:[1,0,1]
	s_waitcnt vmcnt(18)
	v_pk_fma_f32 v[0:1], v[12:13], v[44:45], v[0:1] op_sel_hi:[1,0,1]
	v_pk_fma_f32 v[2:3], v[14:15], v[44:45], v[2:3] op_sel_hi:[1,0,1]
	s_waitcnt vmcnt(17)
	v_pk_fma_f32 v[0:1], v[16:17], v[48:49], v[0:1] op_sel_hi:[1,0,1]
	v_pk_fma_f32 v[2:3], v[18:19], v[48:49], v[2:3] op_sel_hi:[1,0,1]
	s_waitcnt vmcnt(15)
	v_pk_fma_f32 v[0:1], v[20:21], v[36:37], v[0:1] op_sel_hi:[1,0,1]
	v_pk_fma_f32 v[2:3], v[22:23], v[36:37], v[2:3] op_sel_hi:[1,0,1]
	s_waitcnt vmcnt(14)
	v_pk_fma_f32 v[0:1], v[24:25], v[40:41], v[0:1] op_sel_hi:[1,0,1]
	v_pk_fma_f32 v[2:3], v[26:27], v[40:41], v[2:3] op_sel_hi:[1,0,1]
	s_waitcnt vmcnt(13)
	v_pk_fma_f32 v[0:1], v[46:47], v[28:29], v[0:1] op_sel_hi:[0,1,1]
	v_pk_fma_f32 v[2:3], v[46:47], v[30:31], v[2:3] op_sel_hi:[0,1,1]
	s_waitcnt vmcnt(12)
	v_pk_fma_f32 v[0:1], v[50:51], v[60:61], v[0:1] op_sel_hi:[0,1,1]
	v_pk_fma_f32 v[2:3], v[50:51], v[62:63], v[2:3] op_sel_hi:[0,1,1]
	s_waitcnt vmcnt(10)
	v_pk_fma_f32 v[0:1], v[52:53], v[64:65], v[0:1] op_sel_hi:[0,1,1]
	v_pk_fma_f32 v[2:3], v[52:53], v[66:67], v[2:3] op_sel_hi:[0,1,1]
	s_waitcnt vmcnt(9)
	v_pk_fma_f32 v[0:1], v[54:55], v[68:69], v[0:1] op_sel_hi:[0,1,1]
	v_pk_fma_f32 v[2:3], v[54:55], v[70:71], v[2:3] op_sel_hi:[0,1,1]
	s_waitcnt vmcnt(8)
	v_pk_fma_f32 v[0:1], v[56:57], v[72:73], v[0:1] op_sel_hi:[0,1,1]
	v_pk_fma_f32 v[2:3], v[56:57], v[74:75], v[2:3] op_sel_hi:[0,1,1]
	s_waitcnt vmcnt(7)
	v_pk_fma_f32 v[0:1], v[58:59], v[76:77], v[0:1] op_sel_hi:[0,1,1]
	v_pk_fma_f32 v[2:3], v[58:59], v[78:79], v[2:3] op_sel_hi:[0,1,1]
	s_waitcnt vmcnt(5)
	v_pk_fma_f32 v[0:1], v[98:99], v[80:81], v[0:1] op_sel_hi:[0,1,1]
	v_pk_fma_f32 v[2:3], v[98:99], v[82:83], v[2:3] op_sel_hi:[0,1,1]
	s_waitcnt vmcnt(4)
	v_pk_fma_f32 v[0:1], v[134:135], v[84:85], v[0:1] op_sel_hi:[0,1,1]
	v_pk_fma_f32 v[2:3], v[134:135], v[86:87], v[2:3] op_sel_hi:[0,1,1]
	s_waitcnt vmcnt(3)
	v_pk_fma_f32 v[0:1], v[136:137], v[88:89], v[0:1] op_sel_hi:[0,1,1]
	v_pk_fma_f32 v[2:3], v[136:137], v[90:91], v[2:3] op_sel_hi:[0,1,1]
	v_pk_fma_f32 v[0:1], v[138:139], v[102:103], v[0:1] op_sel_hi:[0,1,1]
	v_pk_fma_f32 v[2:3], v[138:139], v[104:105], v[2:3] op_sel_hi:[0,1,1]
	v_pk_fma_f32 v[0:1], v[140:141], v[106:107], v[0:1] op_sel_hi:[0,1,1]
	v_pk_fma_f32 v[2:3], v[140:141], v[108:109], v[2:3] op_sel_hi:[0,1,1]
	v_pk_fma_f32 v[0:1], v[142:143], v[110:111], v[0:1] op_sel_hi:[0,1,1]
	v_pk_fma_f32 v[2:3], v[142:143], v[112:113], v[2:3] op_sel_hi:[0,1,1]
	v_pk_fma_f32 v[0:1], v[144:145], v[114:115], v[0:1] op_sel_hi:[0,1,1]
	v_pk_fma_f32 v[2:3], v[144:145], v[116:117], v[2:3] op_sel_hi:[0,1,1]
	v_pk_fma_f32 v[0:1], v[146:147], v[118:119], v[0:1] op_sel_hi:[0,1,1]
	v_pk_fma_f32 v[2:3], v[146:147], v[120:121], v[2:3] op_sel_hi:[0,1,1]
	v_pk_fma_f32 v[0:1], v[148:149], v[122:123], v[0:1] op_sel_hi:[0,1,1]
	v_pk_fma_f32 v[2:3], v[148:149], v[124:125], v[2:3] op_sel_hi:[0,1,1]
	s_waitcnt vmcnt(2)
	v_pk_fma_f32 v[0:1], v[150:151], v[126:127], v[0:1] op_sel_hi:[0,1,1]
	v_pk_fma_f32 v[2:3], v[150:151], v[128:129], v[2:3] op_sel_hi:[0,1,1]
	s_waitcnt vmcnt(1)
	v_pk_fma_f32 v[0:1], v[152:153], v[130:131], v[0:1] op_sel_hi:[0,1,1]
	v_pk_fma_f32 v[2:3], v[152:153], v[132:133], v[2:3] op_sel_hi:[0,1,1]
	s_waitcnt vmcnt(0)
	v_pk_fma_f32 v[0:1], v[184:185], v[92:93], v[0:1] op_sel_hi:[0,1,1]
	v_pk_fma_f32 v[2:3], v[184:185], v[94:95], v[2:3] op_sel_hi:[0,1,1]
	ds_bpermute_b32 v4, v153, v0
	ds_bpermute_b32 v5, v153, v1
	ds_bpermute_b32 v6, v153, v2
	ds_bpermute_b32 v7, v153, v3
	v_add_f32_e32 v8, v33, v35
	ds_bpermute_b32 v9, v101, v8
	s_waitcnt lgkmcnt(3)
	v_pk_add_f32 v[0:1], v[0:1], v[4:5]
	ds_bpermute_b32 v4, v101, v0
	s_waitcnt lgkmcnt(2)
	v_pk_add_f32 v[2:3], v[2:3], v[6:7]
	ds_bpermute_b32 v5, v101, v1
	ds_bpermute_b32 v6, v101, v2
	ds_bpermute_b32 v7, v101, v3
	s_and_saveexec_b64 s[4:5], s[38:39]
	s_cbranch_execz .LBB0_567
	s_waitcnt lgkmcnt(2)
	v_pk_add_f32 v[0:1], v[0:1], v[4:5]
	s_waitcnt lgkmcnt(0)
	v_pk_add_f32 v[2:3], v[2:3], v[6:7]
	ds_write_b128 v180, v[0:3] offset:8192
